# attention: first 8 V transposed reads + next-tile address calc hoisted under the P pack (after last QK MFMA)
# baseline (speedup 1.0000x reference)
.LBB0_215:
	v_lshl_add_u64 v[150:151], v[148:149], 0, s[58:59]
	ds_read_b128 v[64:67], v181 offset:49152
	ds_read_b128 v[68:71], v181 offset:57344
	v_add_f32_e32 v128, 0, v234
	v_add_f32_e32 v128, v235, v128
	v_add_f32_e32 v128, v236, v128
	s_waitcnt lgkmcnt(1)
	v_mfma_f32_32x32x16_bf16 v[80:95], v[64:67], v[108:111], 0
	v_add_f32_e32 v128, v237, v128
	v_add_f32_e32 v128, v238, v128
	ds_read_b128 v[202:205], v182 offset:49152
	ds_read_b128 v[206:209], v182 offset:57344
	v_add_f32_e32 v128, v239, v128
	v_add_f32_e32 v128, v240, v128
	v_add_f32_e32 v128, v241, v128
	v_add_f32_e32 v128, v242, v128
	s_waitcnt lgkmcnt(2)
	v_mfma_f32_32x32x16_bf16 v[64:79], v[68:71], v[108:111], 0
	v_add_f32_e32 v128, v243, v128
	v_add_f32_e32 v128, v244, v128
	v_add_f32_e32 v128, v245, v128
	v_add_f32_e32 v128, v246, v128
	v_add_f32_e32 v128, v247, v128
	v_add_f32_e32 v128, v252, v128
	v_add_f32_e32 v128, v253, v128
	s_waitcnt lgkmcnt(1)
	v_mfma_f32_32x32x16_bf16 v[80:95], v[202:205], v[104:107], v[80:95]
	v_add_f32_e32 v128, v218, v128
	v_add_f32_e32 v128, v219, v128
	v_add_f32_e32 v128, v220, v128
	v_add_f32_e32 v128, v221, v128
	v_add_f32_e32 v128, v222, v128
	v_add_f32_e32 v128, v223, v128
	v_add_f32_e32 v128, v224, v128
	s_waitcnt lgkmcnt(0)
	v_mfma_f32_32x32x16_bf16 v[64:79], v[206:209], v[104:107], v[64:79]
	ds_read_b128 v[202:205], v183 offset:49152
	ds_read_b128 v[206:209], v183 offset:57344
	v_add_f32_e32 v128, v225, v128
	v_add_f32_e32 v128, v226, v128
	v_add_f32_e32 v128, v227, v128
	v_add_f32_e32 v128, v228, v128
	v_add_f32_e32 v128, v229, v128
	v_add_f32_e32 v128, v230, v128
	s_waitcnt lgkmcnt(1)
	v_mfma_f32_32x32x16_bf16 v[80:95], v[202:205], v[100:103], v[80:95]
	v_add_f32_e32 v128, v231, v128
	v_add_f32_e32 v128, v232, v128
	v_add_f32_e32 v187, v233, v128
	v_mov_b32_e32 v188, v187
	v_lshl_add_u64 v[152:153], v[146:147], 0, s[58:59]
	s_nop 0
	v_permlane32_swap_b32_e32 v187, v188
	s_waitcnt lgkmcnt(0)
	v_mfma_f32_32x32x16_bf16 v[64:79], v[206:209], v[100:103], v[64:79]
	ds_read_b128 v[202:205], v184 offset:49152
	ds_read_b128 v[206:209], v184 offset:57344
	v_cvt_pk_bf16_f32 v128, v234, v235
	v_cvt_pk_bf16_f32 v129, v236, v237
	v_cvt_pk_bf16_f32 v130, v238, v239
	v_cvt_pk_bf16_f32 v131, v240, v241
	v_cvt_pk_bf16_f32 v198, v242, v243
	v_cvt_pk_bf16_f32 v199, v244, v245
	s_waitcnt lgkmcnt(1)
	v_mfma_f32_32x32x16_bf16 v[80:95], v[202:205], v[96:99], v[80:95]
	v_permlane32_swap_b32_e32 v128, v130
	v_cvt_pk_bf16_f32 v200, v246, v247
	v_cvt_pk_bf16_f32 v201, v252, v253
	v_cvt_pk_bf16_f32 v190, v218, v219
	v_cvt_pk_bf16_f32 v191, v220, v221
	v_cvt_pk_bf16_f32 v192, v222, v223
	s_waitcnt lgkmcnt(0)
	v_mfma_f32_32x32x16_bf16 v[64:79], v[206:209], v[96:99], v[64:79]
	v_add_co_u32_e32 v116, vcc, s86, v152
	s_nop 1
	v_addc_co_u32_e32 v117, vcc, 0, v153, vcc
	v_add_co_u32_e32 v120, vcc, s86, v150
	s_nop 1
	v_addc_co_u32_e32 v121, vcc, 0, v151, vcc
	ds_read_b64_tr_b16 v[202:203], v177 offset:0
	ds_read_b64_tr_b16 v[204:205], v177 offset:0x800
	ds_read_b64_tr_b16 v[206:207], v177 offset:0x1000
	ds_read_b64_tr_b16 v[208:209], v177 offset:0x1800
	ds_read_b64_tr_b16 v[210:211], v177 offset:0x2000
	ds_read_b64_tr_b16 v[212:213], v177 offset:0x2800
	ds_read_b64_tr_b16 v[214:215], v177 offset:0x3000
	ds_read_b64_tr_b16 v[216:217], v177 offset:0x3800
	v_cvt_pk_bf16_f32 v193, v224, v225
	v_cvt_pk_bf16_f32 v194, v226, v227
	v_cvt_pk_bf16_f32 v195, v228, v229
	v_cvt_pk_bf16_f32 v196, v230, v231
	v_cvt_pk_bf16_f32 v197, v232, v233
	v_permlane32_swap_b32_e32 v129, v131
	v_permlane32_swap_b32_e32 v198, v200
	v_permlane32_swap_b32_e32 v199, v201
	v_permlane32_swap_b32_e32 v190, v192
	v_permlane32_swap_b32_e32 v191, v193
	v_permlane32_swap_b32_e32 v194, v196
	v_permlane32_swap_b32_e32 v195, v197
	global_load_dwordx4 v[112:115], v[116:117], off offset:1024
	s_nop 0
	global_load_dwordx4 v[116:119], v[116:117], off
	s_nop 0
	global_load_dwordx4 v[124:127], v[120:121], off offset:1024
	s_nop 0
	global_load_dwordx4 v[120:123], v[120:121], off
	s_waitcnt lgkmcnt(0)
	s_nop 0
	v_mfma_f32_32x32x16_bf16 v[0:15], v[128:131], v[202:205], v[0:15]
	ds_read_b64_tr_b16 v[202:203], v177 offset:0x200
	ds_read_b64_tr_b16 v[204:205], v177 offset:0xa00
	v_max_f32_e32 v250, v81, v81
	v_max_f32_e32 v251, v80, v80
	v_max_f32_e32 v250, v251, v250
	v_max3_f32 v250, v250, v82, v83
	v_max3_f32 v250, v250, v84, v85
	v_max3_f32 v250, v250, v86, v87
	v_max3_f32 v250, v250, v88, v89
	v_max3_f32 v250, v250, v90, v91
	v_max3_f32 v250, v250, v92, v93
	v_mfma_f32_32x32x16_bf16 v[0:15], v[198:201], v[206:209], v[0:15]
	ds_read_b64_tr_b16 v[206:207], v177 offset:0x1200
	ds_read_b64_tr_b16 v[208:209], v177 offset:0x1a00
	v_max3_f32 v250, v250, v94, v95
	v_max3_f32 v250, v250, v64, v65
	v_max3_f32 v250, v250, v66, v67
	v_max3_f32 v250, v250, v68, v69
	v_max3_f32 v250, v250, v70, v71
	v_max3_f32 v250, v250, v72, v73
	v_max3_f32 v250, v250, v74, v75
	v_max3_f32 v250, v250, v76, v77
	v_max3_f32 v250, v250, v78, v79
	v_mfma_f32_32x32x16_bf16 v[0:15], v[190:193], v[210:213], v[0:15]
	ds_read_b64_tr_b16 v[210:211], v177 offset:0x2200
	ds_read_b64_tr_b16 v[212:213], v177 offset:0x2a00
	v_mov_b32_e32 v251, v250
	s_nop 1
	v_permlane32_swap_b32_e32 v250, v251
	v_max_f32_e32 v251, v251, v251
	v_max_f32_e32 v250, v250, v250
	v_max_f32_e32 v250, v250, v251
	v_sub_f32_e32 v251, v250, v186
	v_cmp_ge_f32_e32 vcc, s33, v251
	v_max_f32_e32 v251, v186, v186
	v_max_f32_e32 v250, v251, v250
	v_mfma_f32_32x32x16_bf16 v[0:15], v[194:197], v[214:217], v[0:15]
	ds_read_b64_tr_b16 v[214:215], v177 offset:0x3200
	ds_read_b64_tr_b16 v[216:217], v177 offset:0x3a00
	v_sub_f32_e32 v251, v186, v250
	v_mul_f32_e32 v251, 0x3e38aa3b, v251
	v_exp_f32_e32 v251, v251
	s_cmp_eq_u64 vcc, exec
	s_cselect_b64 s[6:7], -1, 0
	v_cndmask_b32_e64 v186, v250, v186, s[6:7]
	v_mul_f32_e32 v254, 0xbe38aa3b, v186
	s_waitcnt lgkmcnt(0)
	v_mfma_f32_32x32x16_bf16 v[48:63], v[128:131], v[202:205], v[48:63]
	ds_read_b64_tr_b16 v[202:203], v177 offset:0x400
	ds_read_b64_tr_b16 v[204:205], v177 offset:0xc00
	v_fmamk_f32 v80, v80, 0x3e38aa3b, v254
	v_fmamk_f32 v81, v81, 0x3e38aa3b, v254
	v_fmamk_f32 v64, v64, 0x3e38aa3b, v254
	v_fmamk_f32 v65, v65, 0x3e38aa3b, v254
	v_exp_f32_e32 v234, v80
	v_exp_f32_e32 v235, v81
	v_fmamk_f32 v82, v82, 0x3e38aa3b, v254
	v_fmamk_f32 v83, v83, 0x3e38aa3b, v254
	v_mfma_f32_32x32x16_bf16 v[48:63], v[198:201], v[206:209], v[48:63]
	ds_read_b64_tr_b16 v[206:207], v177 offset:0x1400
	ds_read_b64_tr_b16 v[208:209], v177 offset:0x1c00
	v_exp_f32_e32 v218, v64
	v_exp_f32_e32 v219, v65
	v_fmamk_f32 v66, v66, 0x3e38aa3b, v254
	v_fmamk_f32 v67, v67, 0x3e38aa3b, v254
	v_exp_f32_e32 v236, v82
	v_mfma_f32_32x32x16_bf16 v[48:63], v[190:193], v[210:213], v[48:63]
	ds_read_b64_tr_b16 v[210:211], v177 offset:0x2400
	ds_read_b64_tr_b16 v[212:213], v177 offset:0x2c00
	v_exp_f32_e32 v237, v83
	v_fmamk_f32 v84, v84, 0x3e38aa3b, v254
	v_fmamk_f32 v85, v85, 0x3e38aa3b, v254
	v_exp_f32_e32 v220, v66
	v_exp_f32_e32 v221, v67
	v_mfma_f32_32x32x16_bf16 v[48:63], v[194:197], v[214:217], v[48:63]
	ds_read_b64_tr_b16 v[214:215], v177 offset:0x3400
	ds_read_b64_tr_b16 v[216:217], v177 offset:0x3c00
	v_fmamk_f32 v68, v68, 0x3e38aa3b, v254
	v_fmamk_f32 v69, v69, 0x3e38aa3b, v254
	v_exp_f32_e32 v238, v84
	v_exp_f32_e32 v239, v85
	v_fmamk_f32 v86, v86, 0x3e38aa3b, v254
	v_fmamk_f32 v87, v87, 0x3e38aa3b, v254
	s_waitcnt lgkmcnt(0)
	v_mfma_f32_32x32x16_bf16 v[32:47], v[128:131], v[202:205], v[32:47]
	ds_read_b64_tr_b16 v[202:203], v177 offset:0x600
	ds_read_b64_tr_b16 v[204:205], v177 offset:0xe00
	v_exp_f32_e32 v222, v68
	v_exp_f32_e32 v223, v69
	v_fmamk_f32 v70, v70, 0x3e38aa3b, v254
	v_fmamk_f32 v71, v71, 0x3e38aa3b, v254
	v_exp_f32_e32 v240, v86
	v_mfma_f32_32x32x16_bf16 v[32:47], v[198:201], v[206:209], v[32:47]
	ds_read_b64_tr_b16 v[206:207], v177 offset:0x1600
	ds_read_b64_tr_b16 v[208:209], v177 offset:0x1e00
	v_exp_f32_e32 v241, v87
	v_fmamk_f32 v88, v88, 0x3e38aa3b, v254
	v_fmamk_f32 v89, v89, 0x3e38aa3b, v254
	v_exp_f32_e32 v224, v70
	v_exp_f32_e32 v225, v71
	v_mfma_f32_32x32x16_bf16 v[32:47], v[190:193], v[210:213], v[32:47]
	ds_read_b64_tr_b16 v[210:211], v177 offset:0x2600
	ds_read_b64_tr_b16 v[212:213], v177 offset:0x2e00
	v_fmamk_f32 v72, v72, 0x3e38aa3b, v254
	v_fmamk_f32 v73, v73, 0x3e38aa3b, v254
	v_exp_f32_e32 v242, v88
	v_exp_f32_e32 v243, v89
	v_fmamk_f32 v90, v90, 0x3e38aa3b, v254
	v_fmamk_f32 v91, v91, 0x3e38aa3b, v254
	v_mfma_f32_32x32x16_bf16 v[32:47], v[194:197], v[214:217], v[32:47]
	ds_read_b64_tr_b16 v[214:215], v177 offset:0x3600
	ds_read_b64_tr_b16 v[216:217], v177 offset:0x3e00
	v_exp_f32_e32 v226, v72
	v_exp_f32_e32 v227, v73
	v_fmamk_f32 v74, v74, 0x3e38aa3b, v254
	v_fmamk_f32 v75, v75, 0x3e38aa3b, v254
	v_exp_f32_e32 v244, v90
	s_waitcnt lgkmcnt(0)
	v_mfma_f32_32x32x16_bf16 v[16:31], v[128:131], v[202:205], v[16:31]
	v_exp_f32_e32 v245, v91
	v_fmamk_f32 v92, v92, 0x3e38aa3b, v254
	v_fmamk_f32 v93, v93, 0x3e38aa3b, v254
	v_exp_f32_e32 v228, v74
	v_exp_f32_e32 v229, v75
	v_mfma_f32_32x32x16_bf16 v[16:31], v[198:201], v[206:209], v[16:31]
	v_fmamk_f32 v76, v76, 0x3e38aa3b, v254
	v_fmamk_f32 v77, v77, 0x3e38aa3b, v254
	v_exp_f32_e32 v246, v92
	v_exp_f32_e32 v247, v93
	v_fmamk_f32 v94, v94, 0x3e38aa3b, v254
	v_fmamk_f32 v95, v95, 0x3e38aa3b, v254
	v_mfma_f32_32x32x16_bf16 v[16:31], v[190:193], v[210:213], v[16:31]
	v_exp_f32_e32 v230, v76
	v_exp_f32_e32 v231, v77
	v_fmamk_f32 v78, v78, 0x3e38aa3b, v254
	v_fmamk_f32 v79, v79, 0x3e38aa3b, v254
	v_exp_f32_e32 v252, v94
	v_mfma_f32_32x32x16_bf16 v[16:31], v[194:197], v[214:217], v[16:31]
	v_exp_f32_e32 v253, v95
	s_nop 0
	v_exp_f32_e32 v232, v78
	v_exp_f32_e32 v233, v79
	s_barrier
	s_waitcnt vmcnt(0)
	v_cndmask_b32_e64 v202, v251, 1.0, s[6:7]
	v_cmp_gt_f32_e32 vcc, 1.0, v202
	s_waitcnt vmcnt(3)
	ds_write_b128 v134, v[112:115]
	s_waitcnt vmcnt(1)
	ds_write_b128 v145, v[124:127]
	ds_write_b128 v175, v[116:119] offset:32768
	s_waitcnt vmcnt(0)
	ds_write_b128 v180, v[120:123] offset:32768
	s_cbranch_vccz .LBB0_219
	s_and_saveexec_b64 s[60:61], s[4:5]
	ds_write_b32 v176, v202 offset:128
	s_or_b64 exec, exec, s[60:61]
	s_waitcnt lgkmcnt(0)
	v_add_u32_e32 v124, v174, v144
	ds_read_b128 v[112:115], v124 offset:224
	ds_read_b128 v[116:119], v124 offset:192
	ds_read_b128 v[120:123], v124 offset:160
	ds_read_b128 v[124:127], v124 offset:128
	s_waitcnt lgkmcnt(3)
	v_pk_mul_f32 v[12:13], v[12:13], v[112:113]
	s_waitcnt lgkmcnt(2)
	v_pk_mul_f32 v[8:9], v[8:9], v[116:117]
	s_waitcnt lgkmcnt(1)
	v_pk_mul_f32 v[4:5], v[4:5], v[120:121]
	v_pk_mul_f32 v[14:15], v[14:15], v[114:115]
	v_pk_mul_f32 v[10:11], v[10:11], v[118:119]
	v_pk_mul_f32 v[6:7], v[6:7], v[122:123]
	s_waitcnt lgkmcnt(0)
	v_pk_mul_f32 v[2:3], v[2:3], v[126:127]
	v_pk_mul_f32 v[0:1], v[0:1], v[124:125]
	v_pk_mul_f32 v[60:61], v[60:61], v[112:113]
	v_pk_mul_f32 v[56:57], v[56:57], v[116:117]
	v_pk_mul_f32 v[52:53], v[52:53], v[120:121]
	v_pk_mul_f32 v[62:63], v[62:63], v[114:115]
	v_pk_mul_f32 v[58:59], v[58:59], v[118:119]
	v_pk_mul_f32 v[54:55], v[54:55], v[122:123]
	v_pk_mul_f32 v[50:51], v[50:51], v[126:127]
	v_pk_mul_f32 v[48:49], v[48:49], v[124:125]
	v_pk_mul_f32 v[44:45], v[44:45], v[112:113]
	v_pk_mul_f32 v[40:41], v[40:41], v[116:117]
	v_pk_mul_f32 v[36:37], v[36:37], v[120:121]
	v_pk_mul_f32 v[46:47], v[46:47], v[114:115]
	v_pk_mul_f32 v[42:43], v[42:43], v[118:119]
	v_pk_mul_f32 v[38:39], v[38:39], v[122:123]
	v_pk_mul_f32 v[34:35], v[34:35], v[126:127]
	v_pk_mul_f32 v[32:33], v[32:33], v[124:125]
	v_pk_mul_f32 v[28:29], v[28:29], v[112:113]
	v_pk_mul_f32 v[24:25], v[24:25], v[116:117]
	v_pk_mul_f32 v[20:21], v[20:21], v[120:121]
	v_pk_mul_f32 v[30:31], v[30:31], v[114:115]
	v_pk_mul_f32 v[26:27], v[26:27], v[118:119]
	v_pk_mul_f32 v[22:23], v[22:23], v[122:123]
	v_pk_mul_f32 v[18:19], v[18:19], v[126:127]
	v_pk_mul_f32 v[16:17], v[16:17], v[124:125]
.LBB0_219:
	s_waitcnt lgkmcnt(0)
	s_barrier
	ds_read_b128 v[64:67], v181 offset:32768
	ds_read_b128 v[68:71], v181 offset:40960
	v_add_f32_e32 v201, 0, v234
	v_add_f32_e32 v201, v235, v201
	v_add_f32_e32 v201, v236, v201
	s_waitcnt lgkmcnt(1)
	v_mfma_f32_32x32x16_bf16 v[80:95], v[64:67], v[108:111], 0
	v_add_f32_e32 v201, v237, v201
	v_add_f32_e32 v201, v238, v201
	ds_read_b128 v[204:207], v182 offset:32768
	ds_read_b128 v[208:211], v182 offset:40960
	v_add_f32_e32 v201, v239, v201
	v_add_f32_e32 v201, v240, v201
	v_add_f32_e32 v201, v241, v201
	v_add_f32_e32 v201, v242, v201
	s_waitcnt lgkmcnt(2)
	v_mfma_f32_32x32x16_bf16 v[64:79], v[68:71], v[108:111], 0
	v_add_f32_e32 v201, v243, v201
	v_add_f32_e32 v201, v244, v201
	v_add_f32_e32 v201, v245, v201
	v_add_f32_e32 v201, v246, v201
	v_add_f32_e32 v201, v247, v201
	v_add_f32_e32 v201, v252, v201
	v_add_f32_e32 v201, v253, v201
	s_waitcnt lgkmcnt(1)
	v_mfma_f32_32x32x16_bf16 v[80:95], v[204:207], v[104:107], v[80:95]
	v_add_f32_e32 v201, v218, v201
	v_add_f32_e32 v201, v219, v201
	v_add_f32_e32 v201, v220, v201
	v_add_f32_e32 v201, v221, v201
	v_add_f32_e32 v201, v222, v201
	v_add_f32_e32 v201, v223, v201
	v_add_f32_e32 v201, v224, v201
	s_waitcnt lgkmcnt(0)
	v_mfma_f32_32x32x16_bf16 v[64:79], v[208:211], v[104:107], v[64:79]
	ds_read_b128 v[204:207], v183 offset:32768
	ds_read_b128 v[208:211], v183 offset:40960
	v_add_f32_e32 v201, v225, v201
	v_add_f32_e32 v201, v226, v201
	v_add_f32_e32 v201, v227, v201
	v_add_f32_e32 v201, v228, v201
	v_add_f32_e32 v201, v229, v201
	v_add_f32_e32 v201, v230, v201
	s_waitcnt lgkmcnt(1)
	v_mfma_f32_32x32x16_bf16 v[80:95], v[204:207], v[100:103], v[80:95]
	v_add_f32_e32 v201, v231, v201
	v_add_f32_e32 v201, v232, v201
	v_add_f32_e32 v203, v233, v201
	s_waitcnt lgkmcnt(0)
	v_mfma_f32_32x32x16_bf16 v[64:79], v[208:211], v[100:103], v[64:79]
	ds_read_b128 v[204:207], v184 offset:32768
	ds_read_b128 v[208:211], v184 offset:40960
	v_cvt_pk_bf16_f32 v128, v234, v235
	v_cvt_pk_bf16_f32 v129, v236, v237
	v_cvt_pk_bf16_f32 v130, v238, v239
	v_cvt_pk_bf16_f32 v131, v240, v241
	v_cvt_pk_bf16_f32 v198, v242, v243
	v_cvt_pk_bf16_f32 v199, v244, v245
	s_waitcnt lgkmcnt(1)
	v_mfma_f32_32x32x16_bf16 v[80:95], v[204:207], v[96:99], v[80:95]
	v_mov_b32_e32 v204, v203
	s_nop 1
	v_permlane32_swap_b32_e32 v203, v204
	v_permlane32_swap_b32_e32 v128, v130
	v_permlane32_swap_b32_e32 v129, v131
	s_waitcnt lgkmcnt(0)
	v_mfma_f32_32x32x16_bf16 v[64:79], v[208:211], v[96:99], v[64:79]
	v_add_co_u32_e32 v116, vcc, s78, v152
	s_nop 1
	v_addc_co_u32_e32 v117, vcc, 0, v153, vcc
	v_add_co_u32_e32 v120, vcc, s78, v150
	s_nop 1
	v_addc_co_u32_e32 v121, vcc, 0, v151, vcc
	ds_read_b64_tr_b16 v[150:151], v179 offset:0
	ds_read_b64_tr_b16 v[152:153], v179 offset:0x800
	ds_read_b64_tr_b16 v[206:207], v179 offset:0x1000
	ds_read_b64_tr_b16 v[208:209], v179 offset:0x1800
	ds_read_b64_tr_b16 v[210:211], v179 offset:0x2000
	ds_read_b64_tr_b16 v[212:213], v179 offset:0x2800
	ds_read_b64_tr_b16 v[214:215], v179 offset:0x3000
	ds_read_b64_tr_b16 v[216:217], v179 offset:0x3800
	v_cvt_pk_bf16_f32 v200, v246, v247
	v_cvt_pk_bf16_f32 v201, v252, v253
	v_cvt_pk_bf16_f32 v190, v218, v219
	v_cvt_pk_bf16_f32 v191, v220, v221
	v_cvt_pk_bf16_f32 v192, v222, v223
	v_cvt_pk_bf16_f32 v193, v224, v225
	v_cvt_pk_bf16_f32 v194, v226, v227
	v_cvt_pk_bf16_f32 v195, v228, v229
	v_cvt_pk_bf16_f32 v196, v230, v231
	v_cvt_pk_bf16_f32 v197, v232, v233
	s_nop 0
	v_permlane32_swap_b32_e32 v198, v200
	v_permlane32_swap_b32_e32 v199, v201
	v_permlane32_swap_b32_e32 v190, v192
	v_permlane32_swap_b32_e32 v191, v193
	v_permlane32_swap_b32_e32 v194, v196
	v_permlane32_swap_b32_e32 v195, v197
	global_load_dwordx4 v[112:115], v[116:117], off offset:1024
	s_nop 0
	global_load_dwordx4 v[116:119], v[116:117], off
	s_nop 0
	global_load_dwordx4 v[124:127], v[120:121], off offset:1024
	s_nop 0
	global_load_dwordx4 v[120:123], v[120:121], off
	s_waitcnt lgkmcnt(0)
	s_nop 0
	v_mfma_f32_32x32x16_bf16 v[0:15], v[128:131], v[150:153], v[0:15]
	ds_read_b64_tr_b16 v[150:151], v179 offset:0x200
	ds_read_b64_tr_b16 v[152:153], v179 offset:0xa00
	v_max_f32_e32 v250, v81, v81
	v_max_f32_e32 v251, v80, v80
	v_max_f32_e32 v250, v251, v250
	v_max3_f32 v250, v250, v82, v83
	v_max3_f32 v250, v250, v84, v85
	v_max3_f32 v250, v250, v86, v87
	v_max3_f32 v250, v250, v88, v89
	v_max3_f32 v250, v250, v90, v91
	v_max3_f32 v250, v250, v92, v93
	v_mfma_f32_32x32x16_bf16 v[0:15], v[198:201], v[206:209], v[0:15]
	ds_read_b64_tr_b16 v[206:207], v179 offset:0x1200
	ds_read_b64_tr_b16 v[208:209], v179 offset:0x1a00
	v_max3_f32 v250, v250, v94, v95
	v_max3_f32 v250, v250, v64, v65
	v_max3_f32 v250, v250, v66, v67
	v_max3_f32 v250, v250, v68, v69
	v_max3_f32 v250, v250, v70, v71
	v_max3_f32 v250, v250, v72, v73
	v_max3_f32 v250, v250, v74, v75
	v_max3_f32 v250, v250, v76, v77
	v_max3_f32 v250, v250, v78, v79
	v_mfma_f32_32x32x16_bf16 v[0:15], v[190:193], v[210:213], v[0:15]
	ds_read_b64_tr_b16 v[210:211], v179 offset:0x2200
	ds_read_b64_tr_b16 v[212:213], v179 offset:0x2a00
	v_mov_b32_e32 v251, v250
	s_nop 1
	v_permlane32_swap_b32_e32 v250, v251
	v_max_f32_e32 v251, v251, v251
	v_max_f32_e32 v250, v250, v250
	v_max_f32_e32 v250, v250, v251
	v_sub_f32_e32 v251, v250, v186
	v_cmp_ge_f32_e32 vcc, s33, v251
	v_max_f32_e32 v251, v186, v186
	v_max_f32_e32 v251, v251, v250
	v_mfma_f32_32x32x16_bf16 v[0:15], v[194:197], v[214:217], v[0:15]
	ds_read_b64_tr_b16 v[214:215], v179 offset:0x3200
	ds_read_b64_tr_b16 v[216:217], v179 offset:0x3a00
	v_sub_f32_e32 v250, v186, v251
	v_mul_f32_e32 v250, 0x3e38aa3b, v250
	v_exp_f32_e32 v250, v250
	s_cmp_eq_u64 vcc, exec
	s_cselect_b64 s[6:7], -1, 0
	v_cndmask_b32_e64 v186, v251, v186, s[6:7]
	v_mul_f32_e32 v254, 0xbe38aa3b, v186
	s_waitcnt lgkmcnt(0)
	v_mfma_f32_32x32x16_bf16 v[48:63], v[128:131], v[150:153], v[48:63]
	ds_read_b64_tr_b16 v[150:151], v179 offset:0x400
	ds_read_b64_tr_b16 v[152:153], v179 offset:0xc00
	v_fmamk_f32 v80, v80, 0x3e38aa3b, v254
	v_fmamk_f32 v81, v81, 0x3e38aa3b, v254
	v_fmamk_f32 v64, v64, 0x3e38aa3b, v254
	v_fmamk_f32 v65, v65, 0x3e38aa3b, v254
	v_exp_f32_e32 v234, v80
	v_exp_f32_e32 v235, v81
	v_fmamk_f32 v82, v82, 0x3e38aa3b, v254
	v_fmamk_f32 v83, v83, 0x3e38aa3b, v254
	v_mfma_f32_32x32x16_bf16 v[48:63], v[198:201], v[206:209], v[48:63]
	ds_read_b64_tr_b16 v[206:207], v179 offset:0x1400
	ds_read_b64_tr_b16 v[208:209], v179 offset:0x1c00
	v_exp_f32_e32 v218, v64
	v_exp_f32_e32 v219, v65
	v_fmamk_f32 v66, v66, 0x3e38aa3b, v254
	v_fmamk_f32 v67, v67, 0x3e38aa3b, v254
	v_exp_f32_e32 v236, v82
	v_mfma_f32_32x32x16_bf16 v[48:63], v[190:193], v[210:213], v[48:63]
	ds_read_b64_tr_b16 v[210:211], v179 offset:0x2400
	ds_read_b64_tr_b16 v[212:213], v179 offset:0x2c00
	v_exp_f32_e32 v237, v83
	v_fmamk_f32 v84, v84, 0x3e38aa3b, v254
	v_fmamk_f32 v85, v85, 0x3e38aa3b, v254
	v_exp_f32_e32 v220, v66
	v_exp_f32_e32 v221, v67
	v_mfma_f32_32x32x16_bf16 v[48:63], v[194:197], v[214:217], v[48:63]
	ds_read_b64_tr_b16 v[214:215], v179 offset:0x3400
	ds_read_b64_tr_b16 v[216:217], v179 offset:0x3c00
	v_fmamk_f32 v68, v68, 0x3e38aa3b, v254
	v_fmamk_f32 v69, v69, 0x3e38aa3b, v254
	v_exp_f32_e32 v238, v84
	v_exp_f32_e32 v239, v85
	v_fmamk_f32 v86, v86, 0x3e38aa3b, v254
	v_fmamk_f32 v87, v87, 0x3e38aa3b, v254
	s_waitcnt lgkmcnt(0)
	v_mfma_f32_32x32x16_bf16 v[32:47], v[128:131], v[150:153], v[32:47]
	ds_read_b64_tr_b16 v[150:151], v179 offset:0x600
	ds_read_b64_tr_b16 v[152:153], v179 offset:0xe00
	v_exp_f32_e32 v222, v68
	v_exp_f32_e32 v223, v69
	v_fmamk_f32 v70, v70, 0x3e38aa3b, v254
	v_fmamk_f32 v71, v71, 0x3e38aa3b, v254
	v_exp_f32_e32 v240, v86
	v_mfma_f32_32x32x16_bf16 v[32:47], v[198:201], v[206:209], v[32:47]
	ds_read_b64_tr_b16 v[206:207], v179 offset:0x1600
	ds_read_b64_tr_b16 v[208:209], v179 offset:0x1e00
	v_exp_f32_e32 v241, v87
	v_fmamk_f32 v88, v88, 0x3e38aa3b, v254
	v_fmamk_f32 v89, v89, 0x3e38aa3b, v254
	v_exp_f32_e32 v224, v70
	v_exp_f32_e32 v225, v71
	v_mfma_f32_32x32x16_bf16 v[32:47], v[190:193], v[210:213], v[32:47]
	ds_read_b64_tr_b16 v[210:211], v179 offset:0x2600
	ds_read_b64_tr_b16 v[212:213], v179 offset:0x2e00
	v_fmamk_f32 v72, v72, 0x3e38aa3b, v254
	v_fmamk_f32 v73, v73, 0x3e38aa3b, v254
	v_exp_f32_e32 v242, v88
	v_exp_f32_e32 v243, v89
	v_fmamk_f32 v90, v90, 0x3e38aa3b, v254
	v_fmamk_f32 v91, v91, 0x3e38aa3b, v254
	v_mfma_f32_32x32x16_bf16 v[32:47], v[194:197], v[214:217], v[32:47]
	ds_read_b64_tr_b16 v[214:215], v179 offset:0x3600
	ds_read_b64_tr_b16 v[216:217], v179 offset:0x3e00
	v_exp_f32_e32 v226, v72
	v_exp_f32_e32 v227, v73
	v_fmamk_f32 v74, v74, 0x3e38aa3b, v254
	v_fmamk_f32 v75, v75, 0x3e38aa3b, v254
	v_exp_f32_e32 v244, v90
	s_waitcnt lgkmcnt(0)
	v_mfma_f32_32x32x16_bf16 v[16:31], v[128:131], v[150:153], v[16:31]
	v_exp_f32_e32 v245, v91
	v_fmamk_f32 v92, v92, 0x3e38aa3b, v254
	v_fmamk_f32 v93, v93, 0x3e38aa3b, v254
	v_exp_f32_e32 v228, v74
	v_exp_f32_e32 v229, v75
	v_mfma_f32_32x32x16_bf16 v[16:31], v[198:201], v[206:209], v[16:31]
	v_fmamk_f32 v76, v76, 0x3e38aa3b, v254
	v_fmamk_f32 v77, v77, 0x3e38aa3b, v254
	v_exp_f32_e32 v246, v92
	v_exp_f32_e32 v247, v93
	v_fmamk_f32 v94, v94, 0x3e38aa3b, v254
	v_fmamk_f32 v95, v95, 0x3e38aa3b, v254
	v_mfma_f32_32x32x16_bf16 v[16:31], v[190:193], v[210:213], v[16:31]
	v_exp_f32_e32 v230, v76
	v_exp_f32_e32 v231, v77
	v_fmamk_f32 v78, v78, 0x3e38aa3b, v254
	v_fmamk_f32 v79, v79, 0x3e38aa3b, v254
	v_exp_f32_e32 v252, v94
	v_mfma_f32_32x32x16_bf16 v[16:31], v[194:197], v[214:217], v[16:31]
	v_exp_f32_e32 v253, v95
	s_nop 0
	v_exp_f32_e32 v232, v78
	v_exp_f32_e32 v233, v79
	s_barrier
	s_waitcnt vmcnt(0)
	v_cndmask_b32_e64 v128, v250, 1.0, s[6:7]
	v_cmp_gt_f32_e32 vcc, 1.0, v128
	s_waitcnt vmcnt(3)
	ds_write_b128 v134, v[112:115] offset:16384
	s_waitcnt vmcnt(1)
	ds_write_b128 v145, v[124:127] offset:16384
	ds_write_b128 v175, v[116:119] offset:49152
	s_waitcnt vmcnt(0)
	ds_write_b128 v180, v[120:123] offset:49152
	s_cbranch_vccz .LBB0_223
	s_and_saveexec_b64 s[60:61], s[4:5]
	ds_write_b32 v176, v128 offset:128
	s_or_b64 exec, exec, s[60:61]
	s_waitcnt lgkmcnt(0)
	v_add_u32_e32 v124, v174, v144
	ds_read_b128 v[112:115], v124 offset:224
	ds_read_b128 v[116:119], v124 offset:192
	ds_read_b128 v[120:123], v124 offset:160
	ds_read_b128 v[124:127], v124 offset:128
	s_waitcnt lgkmcnt(3)
	v_pk_mul_f32 v[12:13], v[12:13], v[112:113]
	s_waitcnt lgkmcnt(2)
	v_pk_mul_f32 v[8:9], v[8:9], v[116:117]
	s_waitcnt lgkmcnt(1)
	v_pk_mul_f32 v[4:5], v[4:5], v[120:121]
	v_pk_mul_f32 v[14:15], v[14:15], v[114:115]
	v_pk_mul_f32 v[10:11], v[10:11], v[118:119]
	v_pk_mul_f32 v[6:7], v[6:7], v[122:123]
	s_waitcnt lgkmcnt(0)
	v_pk_mul_f32 v[2:3], v[2:3], v[126:127]
	v_pk_mul_f32 v[0:1], v[0:1], v[124:125]
	v_pk_mul_f32 v[60:61], v[60:61], v[112:113]
	v_pk_mul_f32 v[56:57], v[56:57], v[116:117]
	v_pk_mul_f32 v[52:53], v[52:53], v[120:121]
	v_pk_mul_f32 v[62:63], v[62:63], v[114:115]
	v_pk_mul_f32 v[58:59], v[58:59], v[118:119]
	v_pk_mul_f32 v[54:55], v[54:55], v[122:123]
	v_pk_mul_f32 v[50:51], v[50:51], v[126:127]
	v_pk_mul_f32 v[48:49], v[48:49], v[124:125]
	v_pk_mul_f32 v[44:45], v[44:45], v[112:113]
	v_pk_mul_f32 v[40:41], v[40:41], v[116:117]
	v_pk_mul_f32 v[36:37], v[36:37], v[120:121]
	v_pk_mul_f32 v[46:47], v[46:47], v[114:115]
	v_pk_mul_f32 v[42:43], v[42:43], v[118:119]
	v_pk_mul_f32 v[38:39], v[38:39], v[122:123]
	v_pk_mul_f32 v[34:35], v[34:35], v[126:127]
	v_pk_mul_f32 v[32:33], v[32:33], v[124:125]
	v_pk_mul_f32 v[28:29], v[28:29], v[112:113]
	v_pk_mul_f32 v[24:25], v[24:25], v[116:117]
	v_pk_mul_f32 v[20:21], v[20:21], v[120:121]
	v_pk_mul_f32 v[30:31], v[30:31], v[114:115]
	v_pk_mul_f32 v[26:27], v[26:27], v[118:119]
	v_pk_mul_f32 v[22:23], v[22:23], v[122:123]
	v_pk_mul_f32 v[18:19], v[18:19], v[126:127]
	v_pk_mul_f32 v[16:17], v[16:17], v[124:125]
